# attention: last key tile of an item reduced to its visible 16-key sub-tile (waves that see nothing of it skip it)
# baseline (speedup 1.0000x reference)
; #define LAS __attribute__((address_space(3)))
; __device__ __forceinline__ unsigned pk2(float lo, float hi) { return pg8::cvt_pk_bf16(lo, hi); }
; __device__ __forceinline__ void att_pv(const LAS unsigned char* Vb, int nst, const f32x4 (&sc)[2][4], f32x4 (&O)[2][8], float& l0, float& l1, int fr, int fq) {
;     ...
;     unsigned pw[2][4][2];
; #pragma unroll
;     for (int st = 0; st < 4; ++st) {
;         if (st < nst) {
;             float p0[4], p1[4];
; #pragma unroll
;             for (int e = 0; e < 4; ++e) { p0[e] = __builtin_amdgcn_exp2f(sc[0][st][e]); p1[e] = __builtin_amdgcn_exp2f(sc[1][st][e]); l0 += p0[e]; l1 += p1[e]; }
;             pw[0][st][0] = pk2(p0[0], p0[1]); pw[0][st][1] = pk2(p0[2], p0[3]); pw[1][st][0] = pk2(p1[0], p1[1]); pw[1][st][1] = pk2(p1[2], p1[3]);
;         } else { pw[0][st][0] = 0u; pw[0][st][1] = 0u; pw[1][st][0] = 0u; pw[1][st][1] = 0u; }
;     }
; #pragma unroll
;     for (int ks2 = 0; ks2 < 2; ++ks2) {
;         if (ks2 == 0 || nst == 4) {
;             const u32x4 a0 = (u32x4){pw[0][2 * ks2][0], pw[0][2 * ks2][1], pw[0][2 * ks2 + 1][0], pw[0][2 * ks2 + 1][1]};
;             const u32x4 a1 = (u32x4){pw[1][2 * ks2][0], pw[1][2 * ks2][1], pw[1][2 * ks2 + 1][0], pw[1][2 * ks2 + 1][1]};
;             const bf16x8 pf0 = __builtin_bit_cast(bf16x8, a0), pf1 = __builtin_bit_cast(bf16x8, a1);
; #pragma unroll
;             for (int dt = 0; dt < 8; ++dt) {
;                 const LAS unsigned char* vp = Vb + (16 * dt + fr) * VSTR + (32 * ks2 + 4 * fq) * 2;
;                 const u32x2 va = *(const LAS u32x2*)vp, vb2 = *(const LAS u32x2*)(vp + 32);
;                 const bf16x8 vf = __builtin_bit_cast(bf16x8, (u32x4){va.x, va.y, vb2.x, vb2.y});
;                 O[0][dt] = __builtin_amdgcn_mfma_f32_16x16x32_bf16(vf, pf0, O[0][dt], 0, 0, 0);
;                 O[1][dt] = __builtin_amdgcn_mfma_f32_16x16x32_bf16(vf, pf1, O[1][dt], 0, 0, 0);
;             }
;         }
.Latt_it_l:
	s_sub_i32 s0, s36, 2
	s_cmp_gt_u32 s0, s37
	s_cbranch_scc1 .Latt_exit
	ds_read_b64 v[6:7], v245 offset:34816
	ds_read_b64 v[8:9], v245 offset:34848
	ds_read_b64 v[10:11], v245 offset:37120
	ds_read_b64 v[12:13], v245 offset:37152
	ds_read_b64 v[14:15], v245 offset:39424
	ds_read_b64 v[16:17], v245 offset:39456
	ds_read_b64 v[18:19], v245 offset:41728
	ds_read_b64 v[20:21], v245 offset:41760
	ds_read_b64 v[22:23], v245 offset:44032
	ds_read_b64 v[24:25], v245 offset:44064
	ds_read_b64 v[26:27], v245 offset:46336
	ds_read_b64 v[28:29], v245 offset:46368
	ds_read_b64 v[30:31], v245 offset:48640
	ds_read_b64 v[32:33], v245 offset:48672
	ds_read_b64 v[34:35], v245 offset:50944
	ds_read_b64 v[36:37], v245 offset:50976
	v_exp_f32_e32 v152, v152
	v_exp_f32_e32 v153, v153
	v_exp_f32_e32 v154, v154
	v_exp_f32_e32 v155, v155
	v_exp_f32_e32 v156, v156
	v_exp_f32_e32 v157, v157
	v_exp_f32_e32 v158, v158
	v_exp_f32_e32 v159, v159
	v_exp_f32_e32 v168, v168
	v_exp_f32_e32 v169, v169
	v_exp_f32_e32 v170, v170
	v_exp_f32_e32 v171, v171
	v_exp_f32_e32 v172, v172
	v_exp_f32_e32 v173, v173
	v_exp_f32_e32 v174, v174
	v_exp_f32_e32 v175, v175
	v_cvt_pk_bf16_f32 v38, v152, v153
	v_cvt_pk_bf16_f32 v39, v154, v155
	v_cvt_pk_bf16_f32 v42, v156, v157
	v_cvt_pk_bf16_f32 v43, v158, v159
	v_pk_add_f32 v[234:235], v[234:235], v[152:153]
	v_pk_add_f32 v[234:235], v[234:235], v[154:155]
	v_pk_add_f32 v[236:237], v[236:237], v[156:157]
	v_pk_add_f32 v[236:237], v[236:237], v[158:159]
	v_cvt_pk_bf16_f32 v40, v168, v169
	v_cvt_pk_bf16_f32 v41, v170, v171
	v_cvt_pk_bf16_f32 v44, v172, v173
	v_cvt_pk_bf16_f32 v45, v174, v175
	v_pk_add_f32 v[234:235], v[234:235], v[168:169]
	v_pk_add_f32 v[234:235], v[234:235], v[170:171]
	v_pk_add_f32 v[236:237], v[236:237], v[172:173]
	v_pk_add_f32 v[236:237], v[236:237], v[174:175]
	s_waitcnt lgkmcnt(12)
	v_mfma_f32_16x16x32_bf16 v[184:187], v[6:9], v[38:41], v[184:187]
	v_mfma_f32_16x16x32_bf16 v[188:191], v[6:9], v[42:45], v[188:191]
	v_mfma_f32_16x16x32_bf16 v[180:183], v[10:13], v[38:41], v[180:183]
	v_mfma_f32_16x16x32_bf16 v[176:179], v[10:13], v[42:45], v[176:179]
	s_waitcnt lgkmcnt(8)
	v_mfma_f32_16x16x32_bf16 v[164:167], v[14:17], v[38:41], v[164:167]
	v_mfma_f32_16x16x32_bf16 v[160:163], v[14:17], v[42:45], v[160:163]
	v_mfma_f32_16x16x32_bf16 v[148:151], v[18:21], v[38:41], v[148:151]
	v_mfma_f32_16x16x32_bf16 v[144:147], v[18:21], v[42:45], v[144:147]
	s_waitcnt lgkmcnt(4)
	v_mfma_f32_16x16x32_bf16 v[140:143], v[22:25], v[38:41], v[140:143]
	v_mfma_f32_16x16x32_bf16 v[136:139], v[22:25], v[42:45], v[136:139]
	v_mfma_f32_16x16x32_bf16 v[132:135], v[26:29], v[38:41], v[132:135]
	v_mfma_f32_16x16x32_bf16 v[124:127], v[26:29], v[42:45], v[124:127]
	s_waitcnt lgkmcnt(0)
	v_mfma_f32_16x16x32_bf16 v[120:123], v[30:33], v[38:41], v[120:123]
	v_mfma_f32_16x16x32_bf16 v[116:119], v[30:33], v[42:45], v[116:119]
	v_mfma_f32_16x16x32_bf16 v[108:111], v[34:37], v[38:41], v[108:111]
	v_mfma_f32_16x16x32_bf16 v[100:103], v[34:37], v[42:45], v[100:103]
